# mixer role split mirrored: pass 1 waves 0-3 gating / waves 4-7 pool, pass 2 swapped
# speedup vs baseline: 1.0138x; 1.0138x over previous
; #define LAS __attribute__((address_space(3)))
; #define tid  (fresh_tid_w(wave_s))
; #define lane (hw_lane())
; __device__ __forceinline__ void pool_load(const bf16* proj, int it, int lane, v4u (&raw)[12]) {
;     const int chunk = it >> 4, g = (it >> 2) & 3, rq = it & 3; proj += (size_t)(chunk >> 6) * GAP_P;
;     const size_t R0 = (size_t)chunk * 128 + rq * 32; const int tseq = (int)(R0 & (SEQ - 1)), r = lane & 15, q = lane >> 4;
; #pragma unroll
;     for (int i = 0; i < 12; ++i) { const int row = q + 4 * i; raw[i] = (v4u){0u, 0u, 0u, 0u};
;         if (row >= 16 || tseq != 0) raw[i] = __builtin_nontemporal_load((const v4u*)(proj + (R0 + row - 16) * DIN + g * 128 + r * 8)); }
; __device__ __forceinline__ void mixer_phase(LAS unsigned char* lds, const bf16* proj, bf16* ymix, const float* vstat, const bf16* WpT, const float* pscale, const float* sgu_g, const bf16* Wm, const float* sgu_b, int pool_first, int pool_step, int pool_limit, int sgu_first, int sgu_step, int sgu_limi ...
;     int tid = tid_in; asm volatile("" : "+v"(tid));
;     const int lane = tid & 63, wave = __builtin_amdgcn_readfirstlane(tid >> 6);
;     LAS unsigned char* wl = lds + wave * MIXW;
;     { v4u raw[12]; if (pool_first < pool_limit) pool_load(proj, pool_first, lane, raw);
;       for (int it = pool_first; it < pool_limit; it += pool_step) pool_item(wl, proj, ymix, WpT, pscale, it >> 4, (it >> 2) & 3, it & 3, lane, raw, it + pool_step < pool_limit ? it + pool_step : -1); }
.LBB0_492:
	s_mov_b64 s[26:27], s[58:59]
	s_mov_b64 s[20:21], s[58:59]
	s_mov_b64 s[38:39], s[58:59]
	v_mbcnt_lo_u32_b32 v0, -1, 0
	v_mbcnt_hi_u32_b32 v0, -1, v0
	s_nop 0
	v_or_b32_e32 v81, s93, v0
	s_nop 0
	s_nop 0
	v_readfirstlane_b32 s0, v81
	s_lshr_b32 s10, s0, 6
	s_lshr_b32 s98, s10, 2
	s_xor_b32 s98, s98, s99
	v_readlane_b32 s0, v254, 42
	v_and_b32_e32 v140, 63, v81
	s_mulk_i32 s10, 0x3300
	v_readlane_b32 s1, v254, 43
	s_add_i32 s2, s10, 0x100
	s_andn2_b64 vcc, exec, s[0:1]
	v_lshlrev_b32_e32 v83, 3, v140
	s_cbranch_vccnz .LBB0_508
	s_cmp_lg_u32 s98, 0
	s_cbranch_scc1 .LBB0_508
	s_add_u32 s9, s26, 0xf100000
	s_addc_u32 s12, s27, 0
	v_readlane_b32 s0, v255, 19
	v_readlane_b32 s6, v254, 46
	s_add_u32 s0, s9, s0
	v_readlane_b32 s1, v255, 18
	v_and_b32_e32 v0, 0x78, v83
	v_readlane_b32 s7, v254, 47
	s_addc_u32 s1, s12, s1
	v_lshrrev_b32_e32 v80, 4, v140
	s_andn2_b64 vcc, exec, s[6:7]
	s_mul_i32 s11, s5, 0xc00
	v_lshlrev_b32_e32 v192, 1, v0
	s_cbranch_vccnz .LBB0_495
	v_or_b32_e32 v4, s4, v80
	v_mov_b64_e32 v[0:1], s[0:1]
	s_movk_i32 s7, 0xc00
	v_mad_u64_u32 v[2:3], s[4:5], v4, s7, v[0:1]
	v_readlane_b32 s4, v254, 48
	v_add_u32_e32 v3, s11, v3
	s_lshl_b32 s86, s4, 1
	v_or_b32_e32 v4, 4, v4
	v_lshl_add_u64 v[2:3], v[2:3], 0, s[86:87]
	v_mad_u64_u32 v[0:1], s[4:5], v4, s7, v[0:1]
	v_lshl_add_u64 v[2:3], v[2:3], 0, v[192:193]
	v_add_u32_e32 v1, s11, v1
	v_add_co_u32_e32 v2, vcc, s83, v2
	v_lshl_add_u64 v[0:1], v[0:1], 0, s[86:87]
	s_nop 0
	v_addc_co_u32_e32 v3, vcc, -1, v3, vcc
	v_lshl_add_u64 v[0:1], v[0:1], 0, v[192:193]
	v_add_co_u32_e32 v4, vcc, 0xffff4000, v0
	s_nop 1
	v_addc_co_u32_e32 v5, vcc, -1, v1, vcc
	global_load_dwordx4 v[0:3], v[2:3], off nt
	s_nop 0
	global_load_dwordx4 v[4:7], v[4:5], off nt
	s_branch .LBB0_496

; #define LAS __attribute__((address_space(3)))
; #define LDS_WAIT() asm volatile("s_waitcnt lgkmcnt(0)" ::: "memory")
; #define lane (hw_lane())
; __device__ __forceinline__ void sgu_item(LAS unsigned char* wl, const bf16* proj, bf16* ymix, const float* vstat, const float* sgu_g, const bf16* Wm, const float* sgu_b, int chunk, int h, int lane) {
;     proj += (size_t)(chunk >> 6) * GAP_P; ymix += (size_t)(chunk >> 6) * GAP_Y;
;     typedef float f32x2 __attribute__((ext_vector_type(2)));
;     const size_t R0 = (size_t)chunk * 128;
;     const int r = lane & 15, q = lane >> 4, c16 = lane & 3, rsub = lane >> 2;
;     LAS f32x2* st = (LAS f32x2*)(wl + 128 * VP2);
; #pragma unroll
;     for (int hh = 0; hh < 2; ++hh) { const f32x4* sp = (const f32x4*)(vstat + (R0 + lane + 64 * hh) * 16);
;         const f32x4 a = sp[0], b = sp[1], c = sp[2], d = sp[3];
;         const float s1 = ((a[0] + a[2]) + (b[0] + b[2])) + ((c[0] + c[2]) + (d[0] + d[2])), s2 = ((a[1] + a[3]) + (b[1] + b[3])) + ((c[1] + c[3]) + (d[1] + d[3]));
;         const float mean = s1 * (1.0f / 512.0f), var = fmaxf(s2 * (1.0f / 512.0f) - mean * mean, 0.f);
;         st[lane + 64 * hh] = (f32x2){mean, __builtin_amdgcn_rsqf(var + EPS)}; }
;     bf16x8 wmf[20];
;     { const bf16* wm = Wm + (size_t)(h * 128 + r) * 128 + q * 8; int f = 0;
; #pragma unroll
;       for (int ks = 0; ks < 4; ++ks)
; #pragma unroll
;         for (int tb = 2 * ks; tb < 8; ++tb) wmf[f++] = *(const bf16x8*)(wm + (size_t)(16 * tb) * 128 + ks * 32); }
;     float bias[8];
; #pragma unroll
;     for (int tb = 0; tb < 8; ++tb) bias[tb] = sgu_b[h * 128 + 16 * tb + r];
;     LDS_WAIT();
; __device__ __forceinline__ void mixer_phase(LAS unsigned char* lds, const bf16* proj, bf16* ymix, const float* vstat, const bf16* WpT, const float* pscale, const float* sgu_g, const bf16* Wm, const float* sgu_b, int pool_first, int pool_step, int pool_limit, int sgu_first, int sgu_step, int sgu_limi ...
;     ...
;     for (int j = sgu_first; j < sgu_limit; j += sgu_step) sgu_item(wl, proj, ymix, vstat, sgu_g, Wm, sgu_b, j >> 2, j & 3, lane);
.LBB0_508:
	v_readlane_b32 s0, v254, 50
	v_readlane_b32 s1, v254, 51
	s_andn2_b64 vcc, exec, s[0:1]
	s_cbranch_vccnz .LBB0_513
	s_cmp_eq_u32 s98, 0
	s_cbranch_scc1 .LBB0_513
	v_readlane_b32 s22, v255, 37
	s_lshl_b32 s86, s22, 9
	v_readlane_b32 s4, v253, 3
	s_lshl_b64 s[0:1], s[86:87], 2
	v_readlane_b32 s14, v253, 13
	v_readlane_b32 s5, v253, 4
	v_readlane_b32 s15, v253, 14
	s_add_u32 s14, s4, s0
	s_waitcnt vmcnt(0)
	v_lshrrev_b32_e32 v0, 1, v81
	v_readlane_b32 s18, v253, 17
	s_addc_u32 s15, s5, s1
	v_and_b32_e32 v2, 24, v0
	v_readlane_b32 s0, v255, 39
	v_readlane_b32 s19, v253, 18
	s_add_u32 s18, s38, 0x25100000
	v_lshlrev_b32_e32 v192, 1, v2
	v_readlane_b32 s1, v255, 40
	s_addc_u32 s19, s39, 0
	v_or_b32_e32 v7, 0x70, v140
	v_lshl_add_u64 v[0:1], s[0:1], 0, v[192:193]
	s_mov_b64 s[0:1], 0x1e40000
	v_lshl_add_u64 v[144:145], v[0:1], 0, s[0:1]
	s_add_u32 s0, s20, 0x10900400
	v_and_b32_e32 v8, 48, v81
	v_and_b32_e32 v143, 15, v81
	v_and_b32_e32 v0, 24, v83
	s_addc_u32 s1, s21, 0
	v_lshl_or_b32 v192, v7, 11, v8
	v_add_u32_e32 v4, s2, v0
	v_bfe_u32 v0, v81, 2, 2
	v_or_b32_e32 v6, 48, v140
	v_lshl_add_u64 v[146:147], s[0:1], 0, v[192:193]
	v_lshl_or_b32 v192, v143, 11, v8
	v_or_b32_e32 v0, v0, v2
	v_lshl_add_u64 v[148:149], s[20:21], 0, v[192:193]
	v_lshl_or_b32 v192, v6, 11, v8
	v_mul_u32_u24_e32 v2, 0x50, v0
	v_lshl_add_u64 v[150:151], s[0:1], 0, v[192:193]
	s_add_u32 s0, s26, 0xf100400
	v_mul_u32_u24_e32 v0, 0xc00, v7
	s_addc_u32 s1, s27, 0
	v_mul_hi_u32_u24_e32 v1, 0xc00, v7
	v_or_b32_e32 v0, v0, v8
	v_lshl_add_u64 v[152:153], s[0:1], 0, v[0:1]
	v_mul_u32_u24_e32 v0, 0xc00, v143
	v_mul_hi_u32_u24_e32 v1, 0xc00, v143
	v_or_b32_e32 v0, v0, v8
	v_lshl_add_u64 v[154:155], s[26:27], 0, v[0:1]
	v_mul_u32_u24_e32 v0, 0xc00, v6
	v_readlane_b32 s23, v255, 38
	v_lshrrev_b32_e32 v3, 2, v140
	v_mul_hi_u32_u24_e32 v1, 0xc00, v6
	v_or_b32_e32 v0, v0, v8
	v_add_u32_e32 v141, s2, v83
	v_lshl_add_u32 v218, v3, 3, s2
	v_lshl_add_u64 v[156:157], s[0:1], 0, v[0:1]
	s_lshl_b64 s[0:1], s[22:23], 11
	v_readlane_b32 s2, v255, 14
	v_mul_u32_u24_e32 v5, 0x50, v3
	v_mul_hi_u32_u24_e32 v1, 0xc00, v3
	v_mul_u32_u24_e32 v0, 0xc00, v3
	v_and_b32_e32 v3, 3, v81
	s_add_u32 s0, s2, s0
	v_readlane_b32 s2, v255, 15
	v_readlane_b32 s7, v253, 6
	v_lshl_or_b32 v0, v3, 4, v0
	v_lshlrev_b32_e32 v192, 5, v3
	s_addc_u32 s1, s2, s1
	v_or_b32_e32 v142, 64, v140
	v_lshl_add_u64 v[158:159], s[26:27], 0, v[0:1]
	v_lshl_add_u64 v[160:161], s[0:1], 0, v[192:193]
	v_add_u32_e32 v219, v4, v5
	v_add_u32_e32 v220, v4, v2
	v_readlane_b32 s4, v254, 62
	v_readlane_b32 s5, v254, 61
	v_readlane_b32 s2, v254, 49
	v_readlane_b32 s7, v254, 63
	v_readlane_b32 s6, v253, 5
	v_readlane_b32 s8, v253, 7
	v_readlane_b32 s9, v253, 8
	v_readlane_b32 s10, v253, 9
	v_readlane_b32 s11, v253, 10
	v_readlane_b32 s12, v253, 11
	v_readlane_b32 s13, v253, 12
	v_readlane_b32 s16, v253, 15
	v_readlane_b32 s17, v253, 16
